# GEMM K-loop: extra s_setprio 0/1 flip after every 8 MFMAs (was every 16)
# baseline (speedup 1.0000x reference)
; #define PG8_STAGE(bufoff, gbase, voff) do { _Pragma("unroll") for (int _i = 0; _i < 2; ++_i) \
;         __builtin_amdgcn_global_load_lds((const unsigned*)((const char*)(gbase) + (voff)[_i]), (LAS unsigned*)(lds + (bufoff) + ldsw + _i * 8192), 16, 0, 0); } while (0)
; #define PG8_LDA(dst, b, h) do { _Pragma("unroll") for (int m = 0; m < 4; ++m) _Pragma("unroll") for (int k = 0; k < 2; ++k) dst[m][k] = *(const LAS bf16x8*)(lds + PG8_SA(b, h) + aoff + m * 2048 + k * 1024); } while (0)
; #define PG8_LDB(dst, b, h) do { _Pragma("unroll") for (int n = 0; n < 2; ++n) _Pragma("unroll") for (int k = 0; k < 2; ++k) dst[n][k] = *(const LAS bf16x8*)(lds + PG8_SB(b, h) + boff + n * 2048 + k * 1024); } while (0)
; #define PG8_MMA(ai, bj, At, Bt) do { __builtin_amdgcn_s_setprio(1); _Pragma("unroll") for (int m = 0; m < 4; ++m) _Pragma("unroll") for (int n = 0; n < 2; ++n) _Pragma("unroll") for (int k = 0; k < 2; ++k) \
;         acc[ai][bj][m][n] = __builtin_amdgcn_mfma_f32_16x16x32_bf16(Bt[n][k], At[m][k], acc[ai][bj][m][n], 0, 0, 0); __builtin_amdgcn_s_setprio(0); } while (0)
; #define PG8_WAIT_V(n) asm volatile("s_waitcnt vmcnt(" #n ")" ::: "memory")
; #define PG8_WAIT_L(n) asm volatile("s_waitcnt lgkmcnt(" #n ")" ::: "memory")
; #define PG8_BAR __builtin_amdgcn_s_barrier()
; #define PG8_SCHED __builtin_amdgcn_sched_barrier(0)
; __device__ __forceinline__ void gemm_phase(LAS unsigned char* lds, const GP p, const int tid) {
;     ...
;             PG8_LDB(B0, 0, 0); PG8_LDB(B1, 0, 1); PG8_SCHED; PG8_LDA(At, 0, 0); PG8_STAGE(PG8_SA(1, 1), a1 + hstep, voffA);
;             PG8_WAIT_V(8); PG8_WAIT_L(0); PG8_BAR; PG8_MMA(0, 0, At, B0); PG8_MMA(0, 1, At, B1); PG8_BAR; PG8_SCHED;
;             PG8_LDA(At, 0, 1); PG8_STAGE(PG8_SB(0, 0), b2, voffB); PG8_STAGE(PG8_SB(0, 1), b2 + hstep, voffB); PG8_STAGE(PG8_SA(0, 0), a2, voffA);
;             PG8_WAIT_V(8); PG8_WAIT_L(0); PG8_BAR; PG8_MMA(1, 0, At, B0); PG8_MMA(1, 1, At, B1); PG8_BAR; PG8_SCHED;
.LBB0_104:
	s_add_i32 s98, s98, 2
	s_add_u32 s43, s82, 0x80
	s_addc_u32 s99, s83, 0
	s_and_b64 s[86:87], s[84:85], exec
	s_cselect_b32 s87, s77, s99
	s_cselect_b32 s86, s76, s43
	s_add_i32 s43, 0, 0x10000
	s_and_b64 s[84:85], s[84:85], exec
	v_add_u32_e32 v142, s43, v165
	s_cselect_b32 s85, s79, s91
	s_cselect_b32 s84, s78, s81
	s_add_i32 s99, 0, 0x14000
	ds_read_b128 v[130:133], v142
	ds_read_b128 v[134:137], v142 offset:1024
	ds_read_b128 v[138:141], v142 offset:2048
	ds_read_b128 v[180:183], v142 offset:3072
	v_add_u32_e32 v142, s99, v165
	ds_read_b128 v[184:187], v142
	ds_read_b128 v[188:191], v142 offset:1024
	ds_read_b128 v[192:195], v142 offset:2048
	ds_read_b128 v[196:199], v142 offset:3072
	v_lshl_add_u64 v[142:143], s[82:83], 0, v[160:161]
	s_add_i32 m0, s53, 0xc000
	ds_read_b128 v[200:203], v167
	ds_read_b128 v[204:207], v167 offset:1024
	ds_read_b128 v[208:211], v167 offset:2048
	ds_read_b128 v[218:221], v167 offset:3072
	ds_read_b128 v[222:225], v167 offset:4096
	ds_read_b128 v[226:229], v167 offset:5120
	ds_read_b128 v[230:233], v167 offset:6144
	ds_read_b128 v[234:237], v167 offset:7168
	global_load_lds_dwordx4 v[142:143], off
	v_lshl_add_u64 v[142:143], s[82:83], 0, v[162:163]
	s_add_i32 m0, s53, 0xe000
	s_nop 0
	global_load_lds_dwordx4 v[142:143], off
	s_waitcnt vmcnt(8)
	s_waitcnt lgkmcnt(0)
	s_barrier
	s_setprio 1
	s_waitcnt lgkmcnt(0)
	v_mfma_f32_16x16x32_bf16 v[124:127], v[130:133], v[200:203], v[124:127]
	v_mfma_f32_16x16x32_bf16 v[120:123], v[138:141], v[200:203], v[120:123]
	v_mfma_f32_16x16x32_bf16 v[108:111], v[130:133], v[208:211], v[108:111]
	v_mfma_f32_16x16x32_bf16 v[104:107], v[138:141], v[208:211], v[104:107]
	v_mfma_f32_16x16x32_bf16 v[92:95], v[130:133], v[222:225], v[92:95]
	v_mfma_f32_16x16x32_bf16 v[88:91], v[138:141], v[222:225], v[88:91]
	v_mfma_f32_16x16x32_bf16 v[76:79], v[130:133], v[230:233], v[76:79]
	v_mfma_f32_16x16x32_bf16 v[72:75], v[138:141], v[230:233], v[72:75]
	s_setprio 0
	s_setprio 1
	v_mfma_f32_16x16x32_bf16 v[124:127], v[134:137], v[204:207], v[124:127]
	v_mfma_f32_16x16x32_bf16 v[120:123], v[180:183], v[204:207], v[120:123]
	v_mfma_f32_16x16x32_bf16 v[108:111], v[134:137], v[218:221], v[108:111]
	v_mfma_f32_16x16x32_bf16 v[104:107], v[180:183], v[218:221], v[104:107]
	v_mfma_f32_16x16x32_bf16 v[92:95], v[134:137], v[226:229], v[92:95]
	v_mfma_f32_16x16x32_bf16 v[88:91], v[180:183], v[226:229], v[88:91]
	v_mfma_f32_16x16x32_bf16 v[76:79], v[134:137], v[234:237], v[76:79]
	v_mfma_f32_16x16x32_bf16 v[72:75], v[180:183], v[234:237], v[72:75]
	s_setprio 0
	s_setprio 1
	v_mfma_f32_16x16x32_bf16 v[116:119], v[184:187], v[200:203], v[116:119]
	v_mfma_f32_16x16x32_bf16 v[112:115], v[192:195], v[200:203], v[112:115]
	v_mfma_f32_16x16x32_bf16 v[100:103], v[184:187], v[208:211], v[100:103]
	v_mfma_f32_16x16x32_bf16 v[96:99], v[192:195], v[208:211], v[96:99]
	v_mfma_f32_16x16x32_bf16 v[84:87], v[184:187], v[222:225], v[84:87]
	v_mfma_f32_16x16x32_bf16 v[80:83], v[192:195], v[222:225], v[80:83]
	v_mfma_f32_16x16x32_bf16 v[68:71], v[184:187], v[230:233], v[68:71]
	v_mfma_f32_16x16x32_bf16 v[64:67], v[192:195], v[230:233], v[64:67]
	s_setprio 0
	s_setprio 1
	v_mfma_f32_16x16x32_bf16 v[116:119], v[188:191], v[204:207], v[116:119]
	v_mfma_f32_16x16x32_bf16 v[112:115], v[196:199], v[204:207], v[112:115]
	v_mfma_f32_16x16x32_bf16 v[100:103], v[188:191], v[218:221], v[100:103]
	v_mfma_f32_16x16x32_bf16 v[96:99], v[196:199], v[218:221], v[96:99]
	v_mfma_f32_16x16x32_bf16 v[84:87], v[188:191], v[226:229], v[84:87]
	v_mfma_f32_16x16x32_bf16 v[80:83], v[196:199], v[226:229], v[80:83]
	v_mfma_f32_16x16x32_bf16 v[68:71], v[188:191], v[234:237], v[68:71]
	v_mfma_f32_16x16x32_bf16 v[64:67], v[196:199], v[234:237], v[64:67]
	s_setprio 0
	s_barrier
	s_add_i32 s43, s43, s52
	v_lshl_add_u64 v[142:143], s[84:85], 0, v[148:149]
	s_mov_b32 m0, s43
	ds_read_b128 v[200:203], v167 offset:16384
	ds_read_b128 v[204:207], v167 offset:17408
	ds_read_b128 v[208:211], v167 offset:18432
	ds_read_b128 v[218:221], v167 offset:19456
	ds_read_b128 v[222:225], v167 offset:20480
	ds_read_b128 v[226:229], v167 offset:21504
	ds_read_b128 v[230:233], v167 offset:22528
	ds_read_b128 v[234:237], v167 offset:23552
	global_load_lds_dwordx4 v[142:143], off
	s_add_i32 m0, s43, 0x2000
	v_lshl_add_u64 v[238:239], s[84:85], 0, v[152:153]
	s_add_u32 s84, s84, s74
	s_addc_u32 s85, s85, 0
	s_add_i32 s43, s99, s52
	global_load_lds_dwordx4 v[238:239], off
	v_lshl_add_u64 v[240:241], s[84:85], 0, v[148:149]
	s_mov_b32 m0, s43
	v_lshl_add_u64 v[242:243], s[84:85], 0, v[152:153]
	global_load_lds_dwordx4 v[240:241], off
	s_add_i32 m0, s43, 0x2000
	v_lshl_add_u64 v[244:245], s[86:87], 0, v[146:147]
	global_load_lds_dwordx4 v[242:243], off
	s_mov_b32 m0, s53
	v_lshl_add_u64 v[246:247], s[86:87], 0, v[150:151]
	global_load_lds_dwordx4 v[244:245], off
	s_mov_b32 m0, s54
	s_nop 0
	global_load_lds_dwordx4 v[246:247], off
	s_waitcnt vmcnt(8)
	s_waitcnt lgkmcnt(0)
	s_barrier
; #define PG8_STAGE(bufoff, gbase, voff) do { _Pragma("unroll") for (int _i = 0; _i < 2; ++_i) \
;         __builtin_amdgcn_global_load_lds((const unsigned*)((const char*)(gbase) + (voff)[_i]), (LAS unsigned*)(lds + (bufoff) + ldsw + _i * 8192), 16, 0, 0); } while (0)
; #define PG8_LDA(dst, b, h) do { _Pragma("unroll") for (int m = 0; m < 4; ++m) _Pragma("unroll") for (int k = 0; k < 2; ++k) dst[m][k] = *(const LAS bf16x8*)(lds + PG8_SA(b, h) + aoff + m * 2048 + k * 1024); } while (0)
; #define PG8_LDB(dst, b, h) do { _Pragma("unroll") for (int n = 0; n < 2; ++n) _Pragma("unroll") for (int k = 0; k < 2; ++k) dst[n][k] = *(const LAS bf16x8*)(lds + PG8_SB(b, h) + boff + n * 2048 + k * 1024); } while (0)
; #define PG8_MMA(ai, bj, At, Bt) do { __builtin_amdgcn_s_setprio(1); _Pragma("unroll") for (int m = 0; m < 4; ++m) _Pragma("unroll") for (int n = 0; n < 2; ++n) _Pragma("unroll") for (int k = 0; k < 2; ++k) \
;         acc[ai][bj][m][n] = __builtin_amdgcn_mfma_f32_16x16x32_bf16(Bt[n][k], At[m][k], acc[ai][bj][m][n], 0, 0, 0); __builtin_amdgcn_s_setprio(0); } while (0)
; #define PG8_WAIT_V(n) asm volatile("s_waitcnt vmcnt(" #n ")" ::: "memory")
; #define PG8_WAIT_L(n) asm volatile("s_waitcnt lgkmcnt(" #n ")" ::: "memory")
; #define PG8_BAR __builtin_amdgcn_s_barrier()
; #define PG8_SCHED __builtin_amdgcn_sched_barrier(0)
; __device__ __forceinline__ void gemm_phase(LAS unsigned char* lds, const GP p, const int tid) {
;     ...
;             PG8_WAIT_V(8); PG8_WAIT_L(0); PG8_BAR; PG8_MMA(1, 0, At, B0); PG8_MMA(1, 1, At, B1); PG8_BAR; PG8_SCHED;
;             PG8_LDB(B0, 1, 0); PG8_LDB(B1, 1, 1); PG8_SCHED; PG8_LDA(At, 1, 0); PG8_STAGE(PG8_SA(0, 1), a2 + hstep, voffA);
;             PG8_WAIT_V(8); PG8_WAIT_L(0); PG8_BAR; PG8_MMA(0, 0, At, B0); PG8_MMA(0, 1, At, B1); PG8_BAR; PG8_SCHED;
;             PG8_LDA(At, 1, 1); PG8_STAGE(PG8_SB(1, 0), b3, voffB); PG8_STAGE(PG8_SB(1, 1), b3 + hstep, voffB); PG8_STAGE(PG8_SA(1, 0), a3, voffA);
;             PG8_WAIT_V(8); PG8_WAIT_L(0); PG8_BAR; PG8_MMA(1, 0, At, B0); PG8_MMA(1, 1, At, B1); PG8_BAR; PG8_SCHED;
	s_setprio 1
	s_waitcnt lgkmcnt(0)
	v_mfma_f32_16x16x32_bf16 v[60:63], v[130:133], v[200:203], v[60:63]
	v_mfma_f32_16x16x32_bf16 v[56:59], v[138:141], v[200:203], v[56:59]
	v_mfma_f32_16x16x32_bf16 v[44:47], v[130:133], v[208:211], v[44:47]
	v_mfma_f32_16x16x32_bf16 v[40:43], v[138:141], v[208:211], v[40:43]
	v_mfma_f32_16x16x32_bf16 v[28:31], v[130:133], v[222:225], v[28:31]
	v_mfma_f32_16x16x32_bf16 v[24:27], v[138:141], v[222:225], v[24:27]
	v_mfma_f32_16x16x32_bf16 v[12:15], v[130:133], v[230:233], v[12:15]
	v_mfma_f32_16x16x32_bf16 v[8:11], v[138:141], v[230:233], v[8:11]
	s_setprio 0
	s_setprio 1
	v_mfma_f32_16x16x32_bf16 v[60:63], v[134:137], v[204:207], v[60:63]
	v_mfma_f32_16x16x32_bf16 v[56:59], v[180:183], v[204:207], v[56:59]
	v_mfma_f32_16x16x32_bf16 v[44:47], v[134:137], v[218:221], v[44:47]
	v_mfma_f32_16x16x32_bf16 v[40:43], v[180:183], v[218:221], v[40:43]
	v_mfma_f32_16x16x32_bf16 v[28:31], v[134:137], v[226:229], v[28:31]
	v_mfma_f32_16x16x32_bf16 v[24:27], v[180:183], v[226:229], v[24:27]
	v_mfma_f32_16x16x32_bf16 v[12:15], v[134:137], v[234:237], v[12:15]
	v_mfma_f32_16x16x32_bf16 v[8:11], v[180:183], v[234:237], v[8:11]
	s_setprio 0
	s_setprio 1
	v_mfma_f32_16x16x32_bf16 v[52:55], v[184:187], v[200:203], v[52:55]
	v_mfma_f32_16x16x32_bf16 v[48:51], v[192:195], v[200:203], v[48:51]
	v_mfma_f32_16x16x32_bf16 v[36:39], v[184:187], v[208:211], v[36:39]
	v_mfma_f32_16x16x32_bf16 v[32:35], v[192:195], v[208:211], v[32:35]
	v_mfma_f32_16x16x32_bf16 v[20:23], v[184:187], v[222:225], v[20:23]
	v_mfma_f32_16x16x32_bf16 v[16:19], v[192:195], v[222:225], v[16:19]
	v_mfma_f32_16x16x32_bf16 v[4:7], v[184:187], v[230:233], v[4:7]
	v_mfma_f32_16x16x32_bf16 v[0:3], v[192:195], v[230:233], v[0:3]
	s_setprio 0
	s_setprio 1
	v_mfma_f32_16x16x32_bf16 v[52:55], v[188:191], v[204:207], v[52:55]
	v_mfma_f32_16x16x32_bf16 v[48:51], v[196:199], v[204:207], v[48:51]
	v_mfma_f32_16x16x32_bf16 v[36:39], v[188:191], v[218:221], v[36:39]
	v_mfma_f32_16x16x32_bf16 v[32:35], v[196:199], v[218:221], v[32:35]
	v_mfma_f32_16x16x32_bf16 v[20:23], v[188:191], v[226:229], v[20:23]
	v_mfma_f32_16x16x32_bf16 v[16:19], v[196:199], v[226:229], v[16:19]
	v_mfma_f32_16x16x32_bf16 v[4:7], v[188:191], v[234:237], v[4:7]
	v_mfma_f32_16x16x32_bf16 v[0:3], v[196:199], v[234:237], v[0:3]
	s_setprio 0
	s_barrier
	s_add_i32 s43, 0, 0x18000
	v_add_u32_e32 v144, s43, v165
	s_add_i32 s99, 0, 0x1c000
	ds_read_b128 v[130:133], v144
	ds_read_b128 v[134:137], v144 offset:1024
	ds_read_b128 v[138:141], v144 offset:2048
	ds_read_b128 v[180:183], v144 offset:3072
	v_add_u32_e32 v144, s99, v165
	ds_read_b128 v[184:187], v144
	ds_read_b128 v[188:191], v144 offset:1024
	ds_read_b128 v[192:195], v144 offset:2048
	ds_read_b128 v[196:199], v144 offset:3072
	s_add_u32 s84, s86, s74
	s_addc_u32 s85, s87, 0
	s_mov_b32 m0, s55
	v_lshl_add_u64 v[248:249], s[84:85], 0, v[146:147]
	ds_read_b128 v[200:203], v167 offset:32768
	ds_read_b128 v[204:207], v167 offset:33792
	ds_read_b128 v[208:211], v167 offset:34816
	ds_read_b128 v[218:221], v167 offset:35840
	ds_read_b128 v[222:225], v167 offset:36864
	ds_read_b128 v[226:229], v167 offset:37888
	ds_read_b128 v[230:233], v167 offset:38912
	ds_read_b128 v[234:237], v167 offset:39936
	global_load_lds_dwordx4 v[248:249], off
	v_lshl_add_u64 v[248:249], s[84:85], 0, v[150:151]
	s_mov_b32 m0, s56
	s_nop 0
	global_load_lds_dwordx4 v[248:249], off
	s_waitcnt vmcnt(8)
	s_waitcnt lgkmcnt(0)
	s_barrier
	s_setprio 1
	s_waitcnt lgkmcnt(0)
	v_mfma_f32_16x16x32_bf16 v[124:127], v[130:133], v[200:203], v[124:127]
	v_mfma_f32_16x16x32_bf16 v[120:123], v[138:141], v[200:203], v[120:123]
	v_mfma_f32_16x16x32_bf16 v[108:111], v[130:133], v[208:211], v[108:111]
	v_mfma_f32_16x16x32_bf16 v[104:107], v[138:141], v[208:211], v[104:107]
	v_mfma_f32_16x16x32_bf16 v[92:95], v[130:133], v[222:225], v[92:95]
	v_mfma_f32_16x16x32_bf16 v[88:91], v[138:141], v[222:225], v[88:91]
	v_mfma_f32_16x16x32_bf16 v[76:79], v[130:133], v[230:233], v[76:79]
	v_mfma_f32_16x16x32_bf16 v[72:75], v[138:141], v[230:233], v[72:75]
	s_setprio 0
	s_setprio 1
	v_mfma_f32_16x16x32_bf16 v[124:127], v[134:137], v[204:207], v[124:127]
	v_mfma_f32_16x16x32_bf16 v[120:123], v[180:183], v[204:207], v[120:123]
	v_mfma_f32_16x16x32_bf16 v[108:111], v[134:137], v[218:221], v[108:111]
	v_mfma_f32_16x16x32_bf16 v[104:107], v[180:183], v[218:221], v[104:107]
	v_mfma_f32_16x16x32_bf16 v[92:95], v[134:137], v[226:229], v[92:95]
	v_mfma_f32_16x16x32_bf16 v[88:91], v[180:183], v[226:229], v[88:91]
	v_mfma_f32_16x16x32_bf16 v[76:79], v[134:137], v[234:237], v[76:79]
	v_mfma_f32_16x16x32_bf16 v[72:75], v[180:183], v[234:237], v[72:75]
	s_setprio 0
	s_setprio 1
	v_mfma_f32_16x16x32_bf16 v[116:119], v[184:187], v[200:203], v[116:119]
	v_mfma_f32_16x16x32_bf16 v[112:115], v[192:195], v[200:203], v[112:115]
	v_mfma_f32_16x16x32_bf16 v[100:103], v[184:187], v[208:211], v[100:103]
	v_mfma_f32_16x16x32_bf16 v[96:99], v[192:195], v[208:211], v[96:99]
	v_mfma_f32_16x16x32_bf16 v[84:87], v[184:187], v[222:225], v[84:87]
	v_mfma_f32_16x16x32_bf16 v[80:83], v[192:195], v[222:225], v[80:83]
	v_mfma_f32_16x16x32_bf16 v[68:71], v[184:187], v[230:233], v[68:71]
	v_mfma_f32_16x16x32_bf16 v[64:67], v[192:195], v[230:233], v[64:67]
	s_setprio 0
	s_setprio 1
	v_mfma_f32_16x16x32_bf16 v[116:119], v[188:191], v[204:207], v[116:119]
	v_mfma_f32_16x16x32_bf16 v[112:115], v[196:199], v[204:207], v[112:115]
	v_mfma_f32_16x16x32_bf16 v[100:103], v[188:191], v[218:221], v[100:103]
	v_mfma_f32_16x16x32_bf16 v[96:99], v[196:199], v[218:221], v[96:99]
	v_mfma_f32_16x16x32_bf16 v[84:87], v[188:191], v[226:229], v[84:87]
	v_mfma_f32_16x16x32_bf16 v[80:83], v[196:199], v[226:229], v[80:83]
	v_mfma_f32_16x16x32_bf16 v[68:71], v[188:191], v[234:237], v[68:71]
	v_mfma_f32_16x16x32_bf16 v[64:67], v[196:199], v[234:237], v[64:67]
	s_setprio 0
	s_barrier
; #define PG8_STAGE(bufoff, gbase, voff) do { _Pragma("unroll") for (int _i = 0; _i < 2; ++_i) \
;         __builtin_amdgcn_global_load_lds((const unsigned*)((const char*)(gbase) + (voff)[_i]), (LAS unsigned*)(lds + (bufoff) + ldsw + _i * 8192), 16, 0, 0); } while (0)
; #define PG8_LDA(dst, b, h) do { _Pragma("unroll") for (int m = 0; m < 4; ++m) _Pragma("unroll") for (int k = 0; k < 2; ++k) dst[m][k] = *(const LAS bf16x8*)(lds + PG8_SA(b, h) + aoff + m * 2048 + k * 1024); } while (0)
; #define PG8_MMA(ai, bj, At, Bt) do { __builtin_amdgcn_s_setprio(1); _Pragma("unroll") for (int m = 0; m < 4; ++m) _Pragma("unroll") for (int n = 0; n < 2; ++n) _Pragma("unroll") for (int k = 0; k < 2; ++k) \
;         acc[ai][bj][m][n] = __builtin_amdgcn_mfma_f32_16x16x32_bf16(Bt[n][k], At[m][k], acc[ai][bj][m][n], 0, 0, 0); __builtin_amdgcn_s_setprio(0); } while (0)
; #define PG8_WAIT_V(n) asm volatile("s_waitcnt vmcnt(" #n ")" ::: "memory")
; #define PG8_WAIT_L(n) asm volatile("s_waitcnt lgkmcnt(" #n ")" ::: "memory")
; #define PG8_BAR __builtin_amdgcn_s_barrier()
; #define PG8_SCHED __builtin_amdgcn_sched_barrier(0)
; __device__ __forceinline__ void gemm_phase(LAS unsigned char* lds, const GP p, const int tid) {
;     ...
;             PG8_LDA(At, 1, 1); PG8_STAGE(PG8_SB(1, 0), b3, voffB); PG8_STAGE(PG8_SB(1, 1), b3 + hstep, voffB); PG8_STAGE(PG8_SA(1, 0), a3, voffA);
;             PG8_WAIT_V(8); PG8_WAIT_L(0); PG8_BAR; PG8_MMA(1, 0, At, B0); PG8_MMA(1, 1, At, B1); PG8_BAR; PG8_SCHED;
	s_add_i32 s43, s43, s52
	v_lshl_add_u64 v[142:143], v[142:143], 0, s[36:37]
	s_mov_b32 m0, s43
	ds_read_b128 v[200:203], v167 offset:49152
	ds_read_b128 v[204:207], v167 offset:50176
	ds_read_b128 v[208:211], v167 offset:51200
	ds_read_b128 v[218:221], v167 offset:52224
	ds_read_b128 v[222:225], v167 offset:53248
	ds_read_b128 v[226:229], v167 offset:54272
	ds_read_b128 v[230:233], v167 offset:55296
	ds_read_b128 v[234:237], v167 offset:56320
	global_load_lds_dwordx4 v[142:143], off
	v_lshl_add_u64 v[142:143], v[238:239], 0, s[36:37]
	s_add_i32 m0, s43, 0x2000
	s_add_i32 s43, s99, s52
	global_load_lds_dwordx4 v[142:143], off
	v_lshl_add_u64 v[142:143], v[240:241], 0, s[36:37]
	s_mov_b32 m0, s43
	s_nop 0
	global_load_lds_dwordx4 v[142:143], off
	v_lshl_add_u64 v[142:143], v[242:243], 0, s[36:37]
	s_add_i32 m0, s43, 0x2000
	s_nop 0
	global_load_lds_dwordx4 v[142:143], off
	v_lshl_add_u64 v[142:143], v[244:245], 0, s[36:37]
	s_mov_b32 m0, s57
	s_nop 0
	global_load_lds_dwordx4 v[142:143], off
	v_lshl_add_u64 v[142:143], v[246:247], 0, s[36:37]
	s_mov_b32 m0, s58
	s_nop 0
	global_load_lds_dwordx4 v[142:143], off
	s_waitcnt vmcnt(8)
	s_waitcnt lgkmcnt(0)
	s_barrier
	s_setprio 1
	s_waitcnt lgkmcnt(0)
	v_mfma_f32_16x16x32_bf16 v[60:63], v[130:133], v[200:203], v[60:63]
	v_mfma_f32_16x16x32_bf16 v[56:59], v[138:141], v[200:203], v[56:59]
	v_mfma_f32_16x16x32_bf16 v[44:47], v[130:133], v[208:211], v[44:47]
	v_mfma_f32_16x16x32_bf16 v[40:43], v[138:141], v[208:211], v[40:43]
	v_mfma_f32_16x16x32_bf16 v[28:31], v[130:133], v[222:225], v[28:31]
	v_mfma_f32_16x16x32_bf16 v[24:27], v[138:141], v[222:225], v[24:27]
	v_mfma_f32_16x16x32_bf16 v[12:15], v[130:133], v[230:233], v[12:15]
	v_mfma_f32_16x16x32_bf16 v[8:11], v[138:141], v[230:233], v[8:11]
	s_setprio 0
	s_setprio 1
	v_mfma_f32_16x16x32_bf16 v[60:63], v[134:137], v[204:207], v[60:63]
	v_mfma_f32_16x16x32_bf16 v[56:59], v[180:183], v[204:207], v[56:59]
	v_mfma_f32_16x16x32_bf16 v[44:47], v[134:137], v[218:221], v[44:47]
	v_mfma_f32_16x16x32_bf16 v[40:43], v[180:183], v[218:221], v[40:43]
	v_mfma_f32_16x16x32_bf16 v[28:31], v[134:137], v[226:229], v[28:31]
	v_mfma_f32_16x16x32_bf16 v[24:27], v[180:183], v[226:229], v[24:27]
	v_mfma_f32_16x16x32_bf16 v[12:15], v[134:137], v[234:237], v[12:15]
	v_mfma_f32_16x16x32_bf16 v[8:11], v[180:183], v[234:237], v[8:11]
	s_setprio 0
	s_setprio 1
	v_mfma_f32_16x16x32_bf16 v[52:55], v[184:187], v[200:203], v[52:55]
	v_mfma_f32_16x16x32_bf16 v[48:51], v[192:195], v[200:203], v[48:51]
	v_mfma_f32_16x16x32_bf16 v[36:39], v[184:187], v[208:211], v[36:39]
	v_mfma_f32_16x16x32_bf16 v[32:35], v[192:195], v[208:211], v[32:35]
	v_mfma_f32_16x16x32_bf16 v[20:23], v[184:187], v[222:225], v[20:23]
	v_mfma_f32_16x16x32_bf16 v[16:19], v[192:195], v[222:225], v[16:19]
	v_mfma_f32_16x16x32_bf16 v[4:7], v[184:187], v[230:233], v[4:7]
	v_mfma_f32_16x16x32_bf16 v[0:3], v[192:195], v[230:233], v[0:3]
	s_setprio 0
	s_setprio 1
	v_mfma_f32_16x16x32_bf16 v[52:55], v[188:191], v[204:207], v[52:55]
	v_mfma_f32_16x16x32_bf16 v[48:51], v[196:199], v[204:207], v[48:51]
	v_mfma_f32_16x16x32_bf16 v[36:39], v[188:191], v[218:221], v[36:39]
	v_mfma_f32_16x16x32_bf16 v[32:35], v[196:199], v[218:221], v[32:35]
	v_mfma_f32_16x16x32_bf16 v[20:23], v[188:191], v[226:229], v[20:23]
	v_mfma_f32_16x16x32_bf16 v[16:19], v[196:199], v[226:229], v[16:19]
	v_mfma_f32_16x16x32_bf16 v[4:7], v[188:191], v[234:237], v[4:7]
	v_mfma_f32_16x16x32_bf16 v[0:3], v[196:199], v[234:237], v[0:3]
	s_setprio 0
	s_barrier
	s_add_u32 s82, s82, 0x100
	s_addc_u32 s83, s83, 0
	s_add_u32 s81, s81, 0x100
	s_addc_u32 s91, s91, 0
	s_cmp_ge_u32 s98, s60
	s_cbranch_scc1 .LBB0_107
